# P0: w_in/w_out transposes rewritten as 256k x 128n workgroup tiles through LDS (xor-swizzled, 512-byte row pieces), streaming (nt) tile loads
# speedup vs baseline: 1.0274x; 1.0097x over previous
.LBB0_22:
	s_or_b64 exec, exec, s[0:1]
	s_lshr_b32 s0, s55, 6
	s_lshl_b32 s1, s2, 3
	v_writelane_b32 v252, s0, 32
	s_add_i32 s13, s0, s1
	v_mbcnt_lo_u32_b32 v38, -1, 0
	v_mbcnt_hi_u32_b32 v38, -1, v38
	v_writelane_b32 v252, s1, 33
	s_cmpk_gt_i32 s13, 0x33ff
	v_lshlrev_b32_e32 v0, 3, v38
	s_cbranch_scc1 .LBB0_77
	v_readlane_b32 s88, v252, 14
	v_readlane_b32 s89, v252, 15
	v_readlane_b32 s90, v252, 10
	v_readlane_b32 s91, v252, 11
	s_lshr_b32 s14, s13, 3
	s_and_b32 s15, s13, 7
	s_lshl_b32 s61, s15, 5
	s_lshl_b32 s62, s15, 2
	v_and_b32_e32 v1, 31, v38
	v_lshrrev_b32_e32 v2, 5, v38
	v_lshlrev_b32_e32 v3, 4, v1
	v_lshlrev_b32_e32 v5, 12, v1
	v_and_b32_e32 v6, 15, v38
	v_lshlrev_b32_e32 v6, 2, v6
	v_xor_b32_e32 v6, v6, v2
	v_lshlrev_b32_e32 v7, 3, v1
	v_lshlrev_b32_e32 v8, 10, v2
	v_lshlrev_b32_e32 v9, 5, v1
	s_mov_b32 s59, 0
.Lp0z_next:
	s_cmpk_lt_u32 s14, 0x300
	s_cbranch_scc0 .Lp0z_nonext
	s_cmpk_lt_u32 s14, 0x200
	s_cbranch_scc0 .Lp0z_wout
	s_lshr_b32 s16, s14, 7
	s_bfe_u32 s17, s14, 0x20005
	s_and_b32 s18, s14, 31
	s_lshl_b32 s19, s16, 24
	s_lshl_b32 s20, s17, 22
	s_add_i32 s19, s19, s20
	s_lshl_b32 s20, s18, 9
	s_add_i32 s19, s19, s20
	s_lshl_b32 s20, s15, 19
	s_add_i32 s19, s19, s20
	s_add_u32 s24, s88, s19
	s_addc_u32 s25, s89, 0
	s_movk_i32 s22, 0x4000
	s_lshl_b32 s19, s16, 12
	s_lshl_b32 s20, s17, 10
	s_add_i32 s19, s19, s20
	s_add_u32 s28, s90, s19
	s_addc_u32 s29, s91, 0
	s_lshr_b32 s19, s18, 3
	s_cmp_eq_u32 s19, 1
	s_cselect_b32 s20, 2, s19
	s_cmp_eq_u32 s19, 2
	s_cselect_b32 s19, 1, s20
	s_lshl_b32 s19, s19, 10
	s_and_b32 s20, s18, 7
	s_lshl_b32 s20, s20, 7
	s_add_i32 s19, s19, s20
	s_lshl_b32 s19, s19, 11
	s_lshl_b32 s20, s17, 9
	s_add_i32 s19, s19, s20
	s_lshl_b32 s20, s16, 23
	s_add_i32 s19, s19, s20
	s_add_i32 s19, s19, 0x400000
	s_lshl_b32 s20, s15, 15
	s_add_i32 s19, s19, s20
	s_add_u32 s56, s10, s19
	s_addc_u32 s57, s11, 0
	s_movk_i32 s58, 0x800
	s_mov_b32 s30, 1
	s_branch .Lp0z_issue
.Lp0z_wout:
	s_sub_i32 s21, s14, 0x200
	s_lshr_b32 s16, s21, 6
	s_bfe_u32 s17, s21, 0x30003
	s_and_b32 s18, s21, 7
	s_lshl_b32 s19, s16, 23
	s_lshl_b32 s20, s17, 20
	s_add_i32 s19, s19, s20
	s_lshl_b32 s20, s18, 9
	s_add_i32 s19, s19, s20
	s_lshl_b32 s20, s15, 17
	s_add_i32 s19, s19, s20
	s_add_u32 s24, s6, s19
	s_addc_u32 s25, s7, 0
	s_movk_i32 s22, 0x1000
	s_lshl_b32 s19, s18, 19
	s_lshl_b32 s20, s17, 9
	s_add_i32 s19, s19, s20
	s_lshl_b32 s20, s16, 22
	s_add_i32 s19, s19, s20
	s_add_i32 s19, s19, 0x2400000
	s_lshl_b32 s20, s15, 16
	s_add_i32 s19, s19, s20
	s_add_u32 s56, s10, s19
	s_addc_u32 s57, s11, 0
	s_movk_i32 s58, 0x1000
	s_mov_b32 s30, 0
.Lp0z_issue:
	v_mul_lo_u32 v4, v2, s22
	v_add_u32_e32 v4, v4, v3
	s_lshl_b32 s64, s22, 1
	global_load_dwordx4 v[64:67], v4, s[24:25] nt
	s_add_u32 s24, s24, s64
	s_addc_u32 s25, s25, 0
	global_load_dwordx4 v[68:71], v4, s[24:25] nt
	s_add_u32 s24, s24, s64
	s_addc_u32 s25, s25, 0
	global_load_dwordx4 v[72:75], v4, s[24:25] nt
	s_add_u32 s24, s24, s64
	s_addc_u32 s25, s25, 0
	global_load_dwordx4 v[76:79], v4, s[24:25] nt
	s_add_u32 s24, s24, s64
	s_addc_u32 s25, s25, 0
	global_load_dwordx4 v[80:83], v4, s[24:25] nt
	s_add_u32 s24, s24, s64
	s_addc_u32 s25, s25, 0
	global_load_dwordx4 v[84:87], v4, s[24:25] nt
	s_add_u32 s24, s24, s64
	s_addc_u32 s25, s25, 0
	global_load_dwordx4 v[88:91], v4, s[24:25] nt
	s_add_u32 s24, s24, s64
	s_addc_u32 s25, s25, 0
	global_load_dwordx4 v[92:95], v4, s[24:25] nt
	s_add_u32 s24, s24, s64
	s_addc_u32 s25, s25, 0
	global_load_dwordx4 v[96:99], v4, s[24:25] nt
	s_add_u32 s24, s24, s64
	s_addc_u32 s25, s25, 0
	global_load_dwordx4 v[100:103], v4, s[24:25] nt
	s_add_u32 s24, s24, s64
	s_addc_u32 s25, s25, 0
	global_load_dwordx4 v[104:107], v4, s[24:25] nt
	s_add_u32 s24, s24, s64
	s_addc_u32 s25, s25, 0
	global_load_dwordx4 v[108:111], v4, s[24:25] nt
	s_add_u32 s24, s24, s64
	s_addc_u32 s25, s25, 0
	global_load_dwordx4 v[112:115], v4, s[24:25] nt
	s_add_u32 s24, s24, s64
	s_addc_u32 s25, s25, 0
	global_load_dwordx4 v[116:119], v4, s[24:25] nt
	s_add_u32 s24, s24, s64
	s_addc_u32 s25, s25, 0
	global_load_dwordx4 v[120:123], v4, s[24:25] nt
	s_add_u32 s24, s24, s64
	s_addc_u32 s25, s25, 0
	global_load_dwordx4 v[124:127], v4, s[24:25] nt
	s_cmp_eq_u32 s30, 0
	s_cbranch_scc1 .Lp0z_one
	global_load_dwordx4 v[148:151], v9, s[28:29]
	global_load_dwordx4 v[152:155], v9, s[28:29] offset:16
	s_branch .Lp0z_issued
.Lp0z_one:
	v_mov_b32_e32 v148, 1.0
	v_mov_b32_e32 v149, 1.0
	v_mov_b32_e32 v150, 1.0
	v_mov_b32_e32 v151, 1.0
	v_mov_b32_e32 v152, 1.0
	v_mov_b32_e32 v153, 1.0
	v_mov_b32_e32 v154, 1.0
	v_mov_b32_e32 v155, 1.0
.Lp0z_issued:
	s_mov_b32 s60, 1
	s_branch .Lp0z_after
.Lp0z_nonext:
	s_mov_b32 s60, 0
.Lp0z_after:
	s_cmp_eq_u32 s59, 0
	s_cbranch_scc1 .Lp0z_advance
	s_waitcnt lgkmcnt(0)
	s_barrier
	s_add_i32 s16, s62, 0
	s_and_b32 s16, s16, 15
	s_lshl_b32 s16, s16, 2
	s_lshl_b32 s17, s15, 4
	s_add_i32 s17, s17, 0
	s_lshl_b32 s17, s17, 10
	v_xor_b32_e32 v11, s16, v7
	v_lshl_add_u32 v11, v11, 2, v8
	v_add_u32_e32 v11, s17, v11
	v_xor_b32_e32 v12, 16, v11
	ds_read_b128 v[156:159], v11
	ds_read_b128 v[160:163], v12
	s_add_i32 s16, s62, 0
	s_and_b32 s16, s16, 15
	s_lshl_b32 s16, s16, 2
	s_lshl_b32 s17, s15, 4
	s_add_i32 s17, s17, 2
	s_lshl_b32 s17, s17, 10
	v_xor_b32_e32 v11, s16, v7
	v_lshl_add_u32 v11, v11, 2, v8
	v_add_u32_e32 v11, s17, v11
	v_xor_b32_e32 v12, 16, v11
	ds_read_b128 v[164:167], v11
	ds_read_b128 v[168:171], v12
	s_add_i32 s16, s62, 1
	s_and_b32 s16, s16, 15
	s_lshl_b32 s16, s16, 2
	s_lshl_b32 s17, s15, 4
	s_add_i32 s17, s17, 4
	s_lshl_b32 s17, s17, 10
	v_xor_b32_e32 v11, s16, v7
	v_lshl_add_u32 v11, v11, 2, v8
	v_add_u32_e32 v11, s17, v11
	v_xor_b32_e32 v12, 16, v11
	ds_read_b128 v[172:175], v11
	ds_read_b128 v[176:179], v12
	s_add_i32 s16, s62, 1
	s_and_b32 s16, s16, 15
	s_lshl_b32 s16, s16, 2
	s_lshl_b32 s17, s15, 4
	s_add_i32 s17, s17, 6
	s_lshl_b32 s17, s17, 10
	v_xor_b32_e32 v11, s16, v7
	v_lshl_add_u32 v11, v11, 2, v8
	v_add_u32_e32 v11, s17, v11
	v_xor_b32_e32 v12, 16, v11
	ds_read_b128 v[180:183], v11
	ds_read_b128 v[184:187], v12
	s_waitcnt lgkmcnt(6)
	v_pk_mul_f32 v[156:157], v[156:157], v[140:141]
	v_pk_mul_f32 v[158:159], v[158:159], v[142:143]
	v_pk_mul_f32 v[160:161], v[160:161], v[144:145]
	v_pk_mul_f32 v[162:163], v[162:163], v[146:147]
	v_cvt_pk_bf16_f32 v128, v156, v157
	v_cvt_pk_bf16_f32 v129, v158, v159
	v_cvt_pk_bf16_f32 v130, v160, v161
	v_cvt_pk_bf16_f32 v131, v162, v163
	global_store_dwordx4 v10, v[128:131], s[26:27]
	s_add_u32 s26, s26, s63
	s_addc_u32 s27, s27, 0
	s_waitcnt lgkmcnt(4)
	v_pk_mul_f32 v[164:165], v[164:165], v[140:141]
	v_pk_mul_f32 v[166:167], v[166:167], v[142:143]
	v_pk_mul_f32 v[168:169], v[168:169], v[144:145]
	v_pk_mul_f32 v[170:171], v[170:171], v[146:147]
	v_cvt_pk_bf16_f32 v132, v164, v165
	v_cvt_pk_bf16_f32 v133, v166, v167
	v_cvt_pk_bf16_f32 v134, v168, v169
	v_cvt_pk_bf16_f32 v135, v170, v171
	global_store_dwordx4 v10, v[132:135], s[26:27]
	s_add_u32 s26, s26, s63
	s_addc_u32 s27, s27, 0
	s_waitcnt lgkmcnt(2)
	v_pk_mul_f32 v[172:173], v[172:173], v[140:141]
	v_pk_mul_f32 v[174:175], v[174:175], v[142:143]
	v_pk_mul_f32 v[176:177], v[176:177], v[144:145]
	v_pk_mul_f32 v[178:179], v[178:179], v[146:147]
	v_cvt_pk_bf16_f32 v128, v172, v173
	v_cvt_pk_bf16_f32 v129, v174, v175
	v_cvt_pk_bf16_f32 v130, v176, v177
	v_cvt_pk_bf16_f32 v131, v178, v179
	global_store_dwordx4 v10, v[128:131], s[26:27]
	s_add_u32 s26, s26, s63
	s_addc_u32 s27, s27, 0
	s_waitcnt lgkmcnt(0)
	v_pk_mul_f32 v[180:181], v[180:181], v[140:141]
	v_pk_mul_f32 v[182:183], v[182:183], v[142:143]
	v_pk_mul_f32 v[184:185], v[184:185], v[144:145]
	v_pk_mul_f32 v[186:187], v[186:187], v[146:147]
	v_cvt_pk_bf16_f32 v132, v180, v181
	v_cvt_pk_bf16_f32 v133, v182, v183
	v_cvt_pk_bf16_f32 v134, v184, v185
	v_cvt_pk_bf16_f32 v135, v186, v187
	global_store_dwordx4 v10, v[132:135], s[26:27]
	s_add_u32 s26, s26, s63
	s_addc_u32 s27, s27, 0
	s_add_i32 s16, s62, 2
	s_and_b32 s16, s16, 15
	s_lshl_b32 s16, s16, 2
	s_lshl_b32 s17, s15, 4
	s_add_i32 s17, s17, 8
	s_lshl_b32 s17, s17, 10
	v_xor_b32_e32 v11, s16, v7
	v_lshl_add_u32 v11, v11, 2, v8
	v_add_u32_e32 v11, s17, v11
	v_xor_b32_e32 v12, 16, v11
	ds_read_b128 v[156:159], v11
	ds_read_b128 v[160:163], v12
	s_add_i32 s16, s62, 2
	s_and_b32 s16, s16, 15
	s_lshl_b32 s16, s16, 2
	s_lshl_b32 s17, s15, 4
	s_add_i32 s17, s17, 10
	s_lshl_b32 s17, s17, 10
	v_xor_b32_e32 v11, s16, v7
	v_lshl_add_u32 v11, v11, 2, v8
	v_add_u32_e32 v11, s17, v11
	v_xor_b32_e32 v12, 16, v11
	ds_read_b128 v[164:167], v11
	ds_read_b128 v[168:171], v12
	s_add_i32 s16, s62, 3
	s_and_b32 s16, s16, 15
	s_lshl_b32 s16, s16, 2
	s_lshl_b32 s17, s15, 4
	s_add_i32 s17, s17, 12
	s_lshl_b32 s17, s17, 10
	v_xor_b32_e32 v11, s16, v7
	v_lshl_add_u32 v11, v11, 2, v8
	v_add_u32_e32 v11, s17, v11
	v_xor_b32_e32 v12, 16, v11
	ds_read_b128 v[172:175], v11
	ds_read_b128 v[176:179], v12
	s_add_i32 s16, s62, 3
	s_and_b32 s16, s16, 15
	s_lshl_b32 s16, s16, 2
	s_lshl_b32 s17, s15, 4
	s_add_i32 s17, s17, 14
	s_lshl_b32 s17, s17, 10
	v_xor_b32_e32 v11, s16, v7
	v_lshl_add_u32 v11, v11, 2, v8
	v_add_u32_e32 v11, s17, v11
	v_xor_b32_e32 v12, 16, v11
	ds_read_b128 v[180:183], v11
	ds_read_b128 v[184:187], v12
	s_waitcnt lgkmcnt(6)
	v_pk_mul_f32 v[156:157], v[156:157], v[140:141]
	v_pk_mul_f32 v[158:159], v[158:159], v[142:143]
	v_pk_mul_f32 v[160:161], v[160:161], v[144:145]
	v_pk_mul_f32 v[162:163], v[162:163], v[146:147]
	v_cvt_pk_bf16_f32 v128, v156, v157
	v_cvt_pk_bf16_f32 v129, v158, v159
	v_cvt_pk_bf16_f32 v130, v160, v161
	v_cvt_pk_bf16_f32 v131, v162, v163
	global_store_dwordx4 v10, v[128:131], s[26:27]
	s_add_u32 s26, s26, s63
	s_addc_u32 s27, s27, 0
	s_waitcnt lgkmcnt(4)
	v_pk_mul_f32 v[164:165], v[164:165], v[140:141]
	v_pk_mul_f32 v[166:167], v[166:167], v[142:143]
	v_pk_mul_f32 v[168:169], v[168:169], v[144:145]
	v_pk_mul_f32 v[170:171], v[170:171], v[146:147]
	v_cvt_pk_bf16_f32 v132, v164, v165
	v_cvt_pk_bf16_f32 v133, v166, v167
	v_cvt_pk_bf16_f32 v134, v168, v169
	v_cvt_pk_bf16_f32 v135, v170, v171
	global_store_dwordx4 v10, v[132:135], s[26:27]
	s_add_u32 s26, s26, s63
	s_addc_u32 s27, s27, 0
	s_waitcnt lgkmcnt(2)
	v_pk_mul_f32 v[172:173], v[172:173], v[140:141]
	v_pk_mul_f32 v[174:175], v[174:175], v[142:143]
	v_pk_mul_f32 v[176:177], v[176:177], v[144:145]
	v_pk_mul_f32 v[178:179], v[178:179], v[146:147]
	v_cvt_pk_bf16_f32 v128, v172, v173
	v_cvt_pk_bf16_f32 v129, v174, v175
	v_cvt_pk_bf16_f32 v130, v176, v177
	v_cvt_pk_bf16_f32 v131, v178, v179
	global_store_dwordx4 v10, v[128:131], s[26:27]
	s_add_u32 s26, s26, s63
	s_addc_u32 s27, s27, 0
	s_waitcnt lgkmcnt(0)
	v_pk_mul_f32 v[180:181], v[180:181], v[140:141]
	v_pk_mul_f32 v[182:183], v[182:183], v[142:143]
	v_pk_mul_f32 v[184:185], v[184:185], v[144:145]
	v_pk_mul_f32 v[186:187], v[186:187], v[146:147]
	v_cvt_pk_bf16_f32 v132, v180, v181
	v_cvt_pk_bf16_f32 v133, v182, v183
	v_cvt_pk_bf16_f32 v134, v184, v185
	v_cvt_pk_bf16_f32 v135, v186, v187
	global_store_dwordx4 v10, v[132:135], s[26:27]
	s_barrier
.Lp0z_advance:
	s_cmp_eq_u32 s60, 0
	s_cbranch_scc1 .Lp0z_done
	s_cmp_eq_u32 s59, 0
	s_cbranch_scc1 .Lp0z_w0
	s_waitcnt vmcnt(8)
	s_branch .Lp0z_landed

.Lp0z_landed:
	s_mov_b64 s[26:27], s[56:57]
	s_mov_b32 s23, s58
	s_lshl_b32 s63, s58, 1
	v_mov_b32_e32 v140, v148
	v_mov_b32_e32 v141, v149
	v_mov_b32_e32 v142, v150
	v_mov_b32_e32 v143, v151
	v_mov_b32_e32 v144, v152
	v_mov_b32_e32 v145, v153
	v_mov_b32_e32 v146, v154
	v_mov_b32_e32 v147, v155
	v_mul_lo_u32 v10, v2, s23
	v_add_u32_e32 v10, v10, v3
	s_add_i32 s16, s61, 0
	v_xor_b32_e32 v11, s16, v6
	v_lshl_add_u32 v11, v11, 2, v5
	ds_write_b32 v11, v64
	ds_write_b32 v11, v65 offset:1024
	ds_write_b32 v11, v66 offset:2048
	ds_write_b32 v11, v67 offset:3072
	s_add_i32 s16, s61, 2
	v_xor_b32_e32 v12, s16, v6
	v_lshl_add_u32 v12, v12, 2, v5
	ds_write_b32 v12, v68
	ds_write_b32 v12, v69 offset:1024
	ds_write_b32 v12, v70 offset:2048
	ds_write_b32 v12, v71 offset:3072
	s_add_i32 s16, s61, 4
	v_xor_b32_e32 v11, s16, v6
	v_lshl_add_u32 v11, v11, 2, v5
	ds_write_b32 v11, v72
	ds_write_b32 v11, v73 offset:1024
	ds_write_b32 v11, v74 offset:2048
	ds_write_b32 v11, v75 offset:3072
	s_add_i32 s16, s61, 6
	v_xor_b32_e32 v12, s16, v6
	v_lshl_add_u32 v12, v12, 2, v5
	ds_write_b32 v12, v76
	ds_write_b32 v12, v77 offset:1024
	ds_write_b32 v12, v78 offset:2048
	ds_write_b32 v12, v79 offset:3072
	s_add_i32 s16, s61, 8
	v_xor_b32_e32 v11, s16, v6
	v_lshl_add_u32 v11, v11, 2, v5
	ds_write_b32 v11, v80
	ds_write_b32 v11, v81 offset:1024
	ds_write_b32 v11, v82 offset:2048
	ds_write_b32 v11, v83 offset:3072
	s_add_i32 s16, s61, 10
	v_xor_b32_e32 v12, s16, v6
	v_lshl_add_u32 v12, v12, 2, v5
	ds_write_b32 v12, v84
	ds_write_b32 v12, v85 offset:1024
	ds_write_b32 v12, v86 offset:2048
	ds_write_b32 v12, v87 offset:3072
	s_add_i32 s16, s61, 12
	v_xor_b32_e32 v11, s16, v6
	v_lshl_add_u32 v11, v11, 2, v5
	ds_write_b32 v11, v88
	ds_write_b32 v11, v89 offset:1024
	ds_write_b32 v11, v90 offset:2048
	ds_write_b32 v11, v91 offset:3072
	s_add_i32 s16, s61, 14
	v_xor_b32_e32 v12, s16, v6
	v_lshl_add_u32 v12, v12, 2, v5
	ds_write_b32 v12, v92
	ds_write_b32 v12, v93 offset:1024
	ds_write_b32 v12, v94 offset:2048
	ds_write_b32 v12, v95 offset:3072
	s_add_i32 s16, s61, 16
	v_xor_b32_e32 v11, s16, v6
	v_lshl_add_u32 v11, v11, 2, v5
	ds_write_b32 v11, v96
	ds_write_b32 v11, v97 offset:1024
	ds_write_b32 v11, v98 offset:2048
	ds_write_b32 v11, v99 offset:3072
	s_add_i32 s16, s61, 18
	v_xor_b32_e32 v12, s16, v6
	v_lshl_add_u32 v12, v12, 2, v5
	ds_write_b32 v12, v100
	ds_write_b32 v12, v101 offset:1024
	ds_write_b32 v12, v102 offset:2048
	ds_write_b32 v12, v103 offset:3072
	s_add_i32 s16, s61, 20
	v_xor_b32_e32 v11, s16, v6
	v_lshl_add_u32 v11, v11, 2, v5
	ds_write_b32 v11, v104
	ds_write_b32 v11, v105 offset:1024
	ds_write_b32 v11, v106 offset:2048
	ds_write_b32 v11, v107 offset:3072
	s_add_i32 s16, s61, 22
	v_xor_b32_e32 v12, s16, v6
	v_lshl_add_u32 v12, v12, 2, v5
	ds_write_b32 v12, v108
	ds_write_b32 v12, v109 offset:1024
	ds_write_b32 v12, v110 offset:2048
	ds_write_b32 v12, v111 offset:3072
	s_add_i32 s16, s61, 24
	v_xor_b32_e32 v11, s16, v6
	v_lshl_add_u32 v11, v11, 2, v5
	ds_write_b32 v11, v112
	ds_write_b32 v11, v113 offset:1024
	ds_write_b32 v11, v114 offset:2048
	ds_write_b32 v11, v115 offset:3072
	s_add_i32 s16, s61, 26
	v_xor_b32_e32 v12, s16, v6
	v_lshl_add_u32 v12, v12, 2, v5
	ds_write_b32 v12, v116
	ds_write_b32 v12, v117 offset:1024
	ds_write_b32 v12, v118 offset:2048
	ds_write_b32 v12, v119 offset:3072
	s_add_i32 s16, s61, 28
	v_xor_b32_e32 v11, s16, v6
	v_lshl_add_u32 v11, v11, 2, v5
	ds_write_b32 v11, v120
	ds_write_b32 v11, v121 offset:1024
	ds_write_b32 v11, v122 offset:2048
	ds_write_b32 v11, v123 offset:3072
	s_add_i32 s16, s61, 30
	v_xor_b32_e32 v12, s16, v6
	v_lshl_add_u32 v12, v12, 2, v5
	ds_write_b32 v12, v124
	ds_write_b32 v12, v125 offset:1024
	ds_write_b32 v12, v126 offset:2048
	ds_write_b32 v12, v127 offset:3072
	s_mov_b32 s59, 1
	s_add_i32 s14, s14, s96
	s_branch .Lp0z_next
.Lp0z_done:
	s_mulk_i32 s0, 0x2200
	s_lshl_b32 s28, s96, 3
	s_add_i32 s0, s0, 0
	s_add_u32 s29, s10, 0x3400000
	s_addc_u32 s30, s11, 0
	s_add_u32 s31, s10, 0x2400000
	s_addc_u32 s33, s11, 0
	s_add_u32 s34, s10, 0x400000
	v_readlane_b32 s36, v252, 16
	s_addc_u32 s35, s11, 0
	v_readlane_b32 s37, v252, 17
	v_readlane_b32 s38, v252, 18
	v_readlane_b32 s39, v252, 19
	v_readlane_b32 s40, v252, 20
	v_readlane_b32 s41, v252, 21
	v_readlane_b32 s42, v252, 22
	v_readlane_b32 s43, v252, 23
	v_readlane_b32 s44, v252, 24
	v_readlane_b32 s45, v252, 25
	v_readlane_b32 s46, v252, 26
	v_readlane_b32 s47, v252, 27
	v_readlane_b32 s48, v252, 28
	v_readlane_b32 s49, v252, 29
	v_readlane_b32 s50, v252, 30
	v_readlane_b32 s51, v252, 31
	v_ashrrev_i32_e32 v1, 5, v38
	v_and_b32_e32 v2, 31, v38
	s_movk_i32 s1, 0x84
	v_ashrrev_i32_e32 v4, 3, v38
	v_and_b32_e32 v8, 56, v0
	s_cmp_lg_u64 s[38:39], 0
	v_readlane_b32 s36, v252, 0
	v_lshl_add_u32 v7, v2, 2, s0
	v_mul_lo_u32 v5, v1, s1
	v_mul_u32_u24_e32 v6, 0x84, v8
	v_lshlrev_b32_e32 v9, 2, v4
	v_readlane_b32 s46, v252, 10
	v_readlane_b32 s47, v252, 11
	v_add_u32_e32 v28, v7, v5
	v_add3_u32 v29, s0, v6, v9
	v_add_u32_e32 v9, 0x108, v5
	v_add_u32_e32 v6, 0x210, v5
	v_add_u32_e32 v10, 0x420, v5
	v_add_u32_e32 v11, 0x630, v5
	v_add_u32_e32 v12, 0x840, v5
	s_cselect_b64 s[14:15], -1, 0
	v_readlane_b32 s37, v252, 1
	v_readlane_b32 s38, v252, 2
	v_readlane_b32 s39, v252, 3
	v_readlane_b32 s40, v252, 4
	v_readlane_b32 s41, v252, 5
	v_readlane_b32 s42, v252, 6
	v_readlane_b32 s43, v252, 7
	v_readlane_b32 s44, v252, 8
	v_readlane_b32 s45, v252, 9
	v_readlane_b32 s48, v252, 12
	v_readlane_b32 s49, v252, 13
	v_readlane_b32 s50, v252, 14
	v_readlane_b32 s51, v252, 15
	s_cmp_lg_u64 s[46:47], 0
	v_mov_b32_e32 v3, 0
	v_add_u32_e32 v30, 8, v4
	v_add_u32_e32 v31, 16, v4
	v_add_u32_e32 v32, 24, v4
	s_cselect_b64 s[16:17], -1, 0
	v_ashrrev_i32_e32 v5, 31, v4
	s_lshl_b32 s36, s13, 5
	s_lshl_b32 s37, s96, 8
	s_lshl_b32 s38, s13, 1
	s_lshl_b32 s39, s96, 4
	s_lshl_b32 s40, s13, 3
	s_lshl_b32 s41, s96, 6
	s_movk_i32 s42, 0x1000
	s_movk_i32 s43, 0x2000
	s_movk_i32 s44, 0x3000
	s_movk_i32 s45, 0x4000
	s_movk_i32 s46, 0x5000
	s_movk_i32 s47, 0x6000
	s_movk_i32 s48, 0x7000
	s_mov_b32 s49, 0x8000
	s_mov_b32 s50, 0xa000
	s_mov_b32 s51, 0xc000
	s_mov_b32 s56, 0xe000
	v_add_u32_e32 v33, v7, v6
	v_add_u32_e32 v34, v7, v11
	v_lshlrev_b32_e32 v6, 2, v2
	v_add_u32_e32 v35, 0x400, v28
	v_add_u32_e32 v36, 0x800, v28
	v_add_u32_e32 v37, 0xc00, v28
	v_add_u32_e32 v39, 0x1000, v28
	v_add_u32_e32 v40, 0x1400, v28
	v_add_u32_e32 v41, 0x1800, v28
	v_add_u32_e32 v42, 0x1c00, v28
	v_lshlrev_b32_e32 v2, 1, v8
	v_add_u32_e32 v43, v7, v9
	v_add_u32_e32 v44, v7, v10
	v_add_u32_e32 v45, v7, v12
	s_mov_b32 s57, 0x10000
	s_mov_b32 s58, 0x18000
	s_mov_b32 s59, 0x20000
	s_mov_b32 s60, 0x28000
	s_mov_b32 s61, 0x30000
	s_mov_b32 s62, 0x38000
	s_mov_b32 s63, 0xe0000
	s_mov_b32 s64, s13
	s_mov_b32 s19, 0
	s_branch .LBB0_27

.LBB0_683:
	s_and_b64 vcc, exec, s[6:7]
	s_cbranch_vccz .LBB0_752
	v_readlane_b32 s16, v253, 38
	v_readlane_b32 s17, v253, 39
	s_mov_b64 s[6:7], -1
	s_and_b64 vcc, exec, s[16:17]
	s_cbranch_vccz .LBB0_701
	v_readlane_b32 s6, v252, 32
	v_readlane_b32 s7, v252, 33
	s_add_i32 s6, s6, s7
	s_cmpk_gt_i32 s6, 0x21ff
	v_mbcnt_lo_u32_b32 v16, -1, 0
	v_mbcnt_hi_u32_b32 v16, -1, v16
	s_cbranch_scc1 .LBB0_700
	s_lshl_b32 s68, s28, 10
	v_readlane_b32 s36, v252, 0
	s_lshl_b64 s[16:17], s[68:69], 2
	v_readlane_b32 s48, v252, 12
	v_lshlrev_b32_e32 v18, 3, v16
	v_readlane_b32 s49, v252, 13
	s_add_u32 s16, s48, s16
	v_ashrrev_i32_e32 v19, 31, v18
	s_addc_u32 s17, s49, s17
	v_lshlrev_b64 v[20:21], 2, v[18:19]
	v_lshl_add_u64 v[12:13], s[16:17], 0, v[20:21]
	global_load_dwordx4 v[0:3], v[12:13], off offset:2064
	global_load_dwordx4 v[4:7], v[12:13], off offset:2048
	global_load_dwordx4 v[8:11], v[12:13], off offset:16
	s_nop 0
	global_load_dwordx4 v[12:15], v[12:13], off
	s_and_b32 s6, s6, 7
	s_lshl_b32 s6, s6, 1
	s_lshr_b32 s7, s2, 6
	s_sub_i32 s7, s7, 1
	s_lshl_b32 s7, s7, 4
	s_add_i32 s6, s6, s7
	s_and_b32 s7, s2, 7
	s_lshl_b32 s7, s7, 3
	s_bfe_u32 s60, s2, 0x30003
	s_or_b32 s7, s7, s60
	s_lshl_b32 s7, s7, 8
	s_add_i32 s6, s6, s7
	s_or_b32 s60, s7, 0xff
	v_readlane_b32 s28, v255, 29
	v_readlane_b32 s38, v252, 2
	v_readlane_b32 s39, v252, 3
	s_cmp_lg_u32 s28, 3
	v_readlane_b32 s40, v252, 4
	v_readlane_b32 s41, v252, 5
	s_cselect_b64 s[38:39], -1, 0
	s_ashr_i32 s7, s6, 31
	s_lshl_b64 s[40:41], s[6:7], 2
	s_lshl_b64 s[16:17], s[6:7], 12
	v_readlane_b32 s21, v255, 3
	s_add_u32 s16, s21, s16
	v_readlane_b32 s21, v255, 4
	v_readlane_b32 s37, v252, 1
	v_lshlrev_b32_e32 v17, 2, v16
	s_addc_u32 s17, s21, s17
	v_xor_b32_e32 v56, 4, v17
	v_xor_b32_e32 v57, 8, v17
	v_xor_b32_e32 v58, 16, v17
	v_xor_b32_e32 v59, 32, v17
	v_xor_b32_e32 v60, 64, v17
	v_xor_b32_e32 v61, 0x80, v17
	v_cmp_eq_u32_e64 s[36:37], 0, v16
	v_lshl_add_u64 v[48:49], s[16:17], 0, v[20:21]
	s_lshl_b64 s[16:17], s[6:7], 11
	v_lshlrev_b64 v[16:17], 1, v[18:19]
	v_lshl_add_u64 v[50:51], s[16:17], 0, v[16:17]
	s_lshl_b64 s[16:17], s[6:7], 13
	v_lshl_add_u64 v[52:53], s[16:17], 0, v[16:17]
	v_readlane_b32 s42, v252, 6
	v_readlane_b32 s43, v252, 7
	v_readlane_b32 s44, v252, 8
	v_readlane_b32 s45, v252, 9
	v_readlane_b32 s46, v252, 10
	v_readlane_b32 s47, v252, 11
	v_readlane_b32 s50, v252, 14
	v_readlane_b32 s51, v252, 15
	v_readlane_b32 s29, v255, 30
	s_branch .LBB0_688
.LBB0_687:
	s_add_i32 s6, s6, 48
	s_add_u32 s40, s40, 0xc0
	s_addc_u32 s41, s41, 0
	s_mov_b32 s16, 0x30000
	s_mov_b32 s17, 0
	v_lshl_add_u64 v[48:49], v[48:49], 0, s[16:17]
	s_mov_b32 s16, 0x18000
	v_lshl_add_u64 v[50:51], v[50:51], 0, s[16:17]
	s_mov_b32 s16, 0x60000
	v_lshl_add_u64 v[52:53], v[52:53], 0, s[16:17]
	s_cmp_gt_i32 s6, s60
	s_cbranch_scc1 .LBB0_700
